# non-temporal loads for the read-once bf16 sub-layer outputs in the post passes, on top of DMA offload to waves 0-3 and progress-based setprio
# baseline (speedup 1.0000x reference)
; #define GAS __attribute__((address_space(1)))
; DI float bf_lo(unsigned u) { return __uint_as_float(u << 16); }
; DI float bf_hi(unsigned u) { return __uint_as_float(u & 0xffff0000u); }
; DI void post_pass(int wv, const bf16_t* raw, long raw_row0, float* x, const float* gpost, const float* gpre, bf16_t* XN, int row_lo, int row_hi, const float* xin_p = nullptr, const float* xin_s = nullptr) {
;     ...
;     for (int row = row_lo + gw; row < row_hi; row += 2 * NGW) {
;         f32x4 v[2][4], xv[2][4]; float s[2] = {0.f, 0.f};
; #pragma unroll
;         for (int q = 0; q < 2; ++q) { const int rw = row + q * NGW;
;             const GAS u32x2* rr = (const GAS u32x2*)(raw + (size_t)(rw - raw_row0) * DM) + lane;
;             const GAS f32x4* xr = (const GAS f32x4*)(xin_p ? (rw < TOK_P ? xin_p + (size_t)rw * DM : xin_s + (size_t)(rw - TOK_P) * DM) : x + (size_t)rw * DM) + lane;
; #pragma unroll
;             for (int j = 0; j < 4; ++j) { const u32x2 w = rr[64 * j]; v[q][j] = (f32x4){bf_lo(w.x), bf_hi(w.x), bf_lo(w.y), bf_hi(w.y)}; xv[q][j] = xr[64 * j]; } }
; #pragma unroll
;         for (int q = 0; q < 2; ++q)
; #pragma unroll
;             for (int j = 0; j < 4; ++j) s[q] += (v[q][j].x * v[q][j].x + v[q][j].y * v[q][j].y) + (v[q][j].z * v[q][j].z + v[q][j].w * v[q][j].w);
; #pragma unroll
;         for (int q = 0; q < 2; ++q) { const int rw = row + q * NGW; GAS f32x4* xr = (GAS f32x4*)(x + (size_t)rw * DM) + lane;
;             const float rstd = __builtin_amdgcn_rsqf(wave_sum(s[q], lane) * (1.0f / DM) + RMS_EPS);
; #pragma unroll
;             for (int j = 0; j < 4; ++j) { const f32x4 gg = ((const GAS f32x4*)gpost)[lane + 64 * j]; xv[q][j] = xv[q][j] + v[q][j] * rstd * gg; xr[64 * j] = xv[q][j]; }
.LBB0_519:
	s_ashr_i32 s7, s6, 31
	s_lshl_b64 s[10:11], s[6:7], 11
	s_add_u32 s8, s18, s10
	s_addc_u32 s9, s19, s11
	v_lshlrev_b32_e32 v35, 3, v16
	global_load_dwordx2 v[0:1], v35, s[8:9] offset:1536 nt
	global_load_dwordx2 v[2:3], v35, s[8:9] nt
	global_load_dwordx2 v[12:13], v35, s[8:9] offset:512 nt
	global_load_dwordx2 v[14:15], v35, s[8:9] offset:1024 nt
	s_lshl_b64 s[8:9], s[6:7], 12
	s_add_u32 s14, s17, s8
	v_lshlrev_b32_e32 v36, 4, v16
	s_addc_u32 s15, s16, s9
	global_load_dwordx4 v[4:7], v[20:21], off
	global_load_dwordx4 v[8:11], v36, s[14:15]
	s_add_i32 s6, s6, s72
	s_ashr_i32 s7, s6, 31
	s_lshl_b64 s[8:9], s[6:7], 11
	s_add_u32 s22, s18, s8
	s_addc_u32 s23, s19, s9
	s_lshl_b64 s[12:13], s[6:7], 12
	s_add_u32 s12, s17, s12
	s_addc_u32 s13, s16, s13
	s_add_u32 s10, s20, s10
	s_addc_u32 s11, s21, s11
	s_add_u32 s8, s20, s8
	s_addc_u32 s9, s21, s9
	s_add_i32 s6, s6, s72
	s_cmp_lt_i32 s6, 0xc000
	s_waitcnt vmcnt(0)
	v_lshlrev_b32_e32 v59, 16, v0
	v_and_b32_e32 v39, 0xffff0000, v2
	v_and_b32_e32 v41, 0xffff0000, v3
	v_and_b32_e32 v61, 0xffff0000, v0
	v_lshlrev_b32_e32 v62, 16, v1
	v_and_b32_e32 v63, 0xffff0000, v1
	v_lshlrev_b32_e32 v38, 16, v2
	v_lshlrev_b32_e32 v40, 16, v3
	v_lshlrev_b32_e32 v46, 16, v12
	v_and_b32_e32 v49, 0xffff0000, v13
	v_and_b32_e32 v48, 0xffff0000, v12
	v_mul_f32_e32 v0, v41, v41
	v_mul_f32_e32 v12, v39, v39
	v_mov_b32_e32 v1, v59
	v_lshlrev_b32_e32 v47, 16, v13
	v_and_b32_e32 v55, 0xffff0000, v14
	v_and_b32_e32 v57, 0xffff0000, v15
	v_pk_mul_f32 v[2:3], v[48:49], v[48:49]
	v_pk_fma_f32 v[24:25], v[40:41], v[40:41], v[0:1] op_sel_hi:[1,1,0]
	v_pk_fma_f32 v[12:13], v[38:39], v[38:39], v[12:13] op_sel_hi:[1,1,0]
	v_lshlrev_b32_e32 v54, 16, v14
	v_lshlrev_b32_e32 v56, 16, v15
	v_mul_f32_e32 v14, v55, v55
	v_mul_f32_e32 v22, v57, v57
	v_pk_fma_f32 v[2:3], v[46:47], v[46:47], v[2:3]
	v_mov_b32_e32 v58, v12
	v_mov_b32_e32 v0, v24
	v_mul_f32_e32 v26, v61, v61
	v_mul_f32_e32 v27, v62, v62
	v_mul_f32_e32 v28, v63, v63
	v_pk_fma_f32 v[14:15], v[54:55], v[54:55], v[14:15] op_sel_hi:[1,1,0]
	v_pk_fma_f32 v[22:23], v[56:57], v[56:57], v[22:23] op_sel_hi:[1,1,0]
	v_pk_add_f32 v[12:13], v[12:13], v[24:25]
	v_pk_add_f32 v[2:3], v[2:3], v[2:3] op_sel:[0,1] op_sel_hi:[1,0]
	v_pk_mul_f32 v[0:1], v[58:59], v[0:1]
	v_mov_b32_e32 v15, v27
	v_mov_b32_e32 v23, v28
	v_mov_b32_e32 v3, v26
	v_mov_b32_e32 v13, v1
	v_pk_add_f32 v[14:15], v[14:15], v[22:23]
	v_pk_add_f32 v[0:1], v[12:13], v[2:3]
	v_mov_b32_e32 v50, v47
	v_pk_add_f32 v[0:1], v[0:1], v[14:15]
	global_load_dwordx4 v[12:15], v36, s[14:15] offset:1024
	v_add_f32_e32 v0, v0, v1
	ds_bpermute_b32 v1, v17, v0
	global_load_dwordx2 v[26:27], v35, s[22:23] nt
	global_load_dwordx2 v[24:25], v35, s[22:23] offset:512 nt
	global_load_dwordx2 v[22:23], v35, s[22:23] offset:1024 nt
	global_load_dwordx2 v[28:29], v35, s[22:23] offset:1536 nt
	v_mov_b32_e32 v51, v49
	v_mov_b32_e32 v47, v48
	s_waitcnt lgkmcnt(0)
	v_add_f32_e32 v0, v0, v1
	ds_bpermute_b32 v1, v30, v0
	v_mov_b32_e32 v60, v59
	s_waitcnt lgkmcnt(0)
	v_add_f32_e32 v0, v0, v1
	ds_bpermute_b32 v1, v31, v0
	s_waitcnt lgkmcnt(0)
	v_add_f32_e32 v0, v0, v1
	ds_bpermute_b32 v1, v32, v0
	s_waitcnt lgkmcnt(0)
	v_add_f32_e32 v0, v0, v1
	ds_bpermute_b32 v1, v33, v0
	s_waitcnt lgkmcnt(0)
	v_add_f32_e32 v0, v0, v1
	ds_bpermute_b32 v1, v34, v0
	s_waitcnt lgkmcnt(0)
	v_add_f32_e32 v0, v0, v1
	v_fmamk_f32 v0, v0, 0x3a800000, v174
	v_rsq_f32_e32 v58, v0
	global_load_dwordx4 v[0:3], v36, s[12:13]
	v_pk_mul_f32 v[38:39], v[58:59], v[38:39] op_sel_hi:[0,1]
	v_pk_mul_f32 v[40:41], v[58:59], v[40:41] op_sel_hi:[0,1]
	v_pk_fma_f32 v[40:41], v[6:7], v[40:41], v[10:11]
	v_pk_fma_f32 v[38:39], v[4:5], v[38:39], v[8:9]
	global_store_dwordx4 v36, v[38:41], s[14:15]
	global_load_dwordx4 v[8:11], v[20:21], off offset:1024
	global_load_dwordx4 v[42:45], v36, s[14:15] offset:2048
	global_load_dwordx4 v[4:7], v36, s[12:13] offset:1024
	v_pk_mul_f32 v[48:49], v[58:59], v[50:51] op_sel_hi:[0,1]
	v_pk_mul_f32 v[46:47], v[58:59], v[46:47] op_sel_hi:[0,1]
	v_pk_mul_f32 v[56:57], v[58:59], v[56:57] op_sel_hi:[0,1]
	v_pk_mul_f32 v[54:55], v[58:59], v[54:55] op_sel_hi:[0,1]
	v_pk_mul_f32 v[60:61], v[58:59], v[60:61] op_sel_hi:[0,1]
	v_pk_mul_f32 v[58:59], v[58:59], v[62:63] op_sel_hi:[0,1]
	s_waitcnt vmcnt(2)
	v_pk_fma_f32 v[46:47], v[8:9], v[46:47], v[12:13]
	v_pk_fma_f32 v[48:49], v[10:11], v[48:49], v[14:15]
	global_store_dwordx4 v36, v[46:49], s[14:15] offset:1024
	global_load_dwordx4 v[12:15], v[20:21], off offset:2048
	global_load_dwordx4 v[50:53], v36, s[14:15] offset:3072
	global_load_dwordx4 v[8:11], v36, s[12:13] offset:2048
	s_waitcnt vmcnt(2)
	v_pk_fma_f32 v[42:43], v[12:13], v[54:55], v[42:43]
	v_pk_fma_f32 v[44:45], v[14:15], v[56:57], v[44:45]
	global_store_dwordx4 v36, v[42:45], s[14:15] offset:2048
	global_load_dwordx4 v[54:57], v[20:21], off offset:3072
	global_load_dwordx4 v[12:15], v36, s[12:13] offset:3072
	s_waitcnt vmcnt(1)
	v_pk_fma_f32 v[52:53], v[56:57], v[58:59], v[52:53]
	v_pk_fma_f32 v[50:51], v[54:55], v[60:61], v[50:51]
	global_store_dwordx4 v36, v[50:53], s[14:15] offset:3072
	global_load_dwordx4 v[54:57], v[18:19], off
	v_pk_mul_f32 v[58:59], v[40:41], v[40:41]
	v_pk_mul_f32 v[60:61], v[38:39], v[38:39]
	s_nop 0
	v_pk_mov_b32 v[62:63], v[60:61], v[58:59] op_sel:[1,0]
	v_mov_b32_e32 v61, v59
	v_pk_add_f32 v[58:59], v[62:63], v[60:61]
	v_pk_mul_f32 v[60:61], v[46:47], v[46:47]
	v_pk_mul_f32 v[62:63], v[48:49], v[48:49]
	v_pk_add_f32 v[58:59], v[58:59], v[58:59] op_sel_hi:[0,1]
	v_pk_mov_b32 v[64:65], v[60:61], v[62:63] op_sel:[1,0]
	v_mov_b32_e32 v61, v63
	v_pk_add_f32 v[60:61], v[64:65], v[60:61]
	v_mul_f32_e32 v58, v42, v42
	v_pk_add_f32 v[60:61], v[60:61], v[60:61] op_sel_hi:[0,1]
	v_mul_f32_e32 v60, v44, v44
	v_pk_fma_f32 v[62:63], v[42:43], v[42:43], v[58:59] op_sel_hi:[1,1,0]
	v_pk_fma_f32 v[64:65], v[44:45], v[44:45], v[60:61] op_sel_hi:[1,1,0]
	v_mul_f32_e32 v62, v50, v50
	v_mul_f32_e32 v64, v51, v51
	v_mul_f32_e32 v58, v52, v52
	v_mul_f32_e32 v60, v53, v53
	v_pk_add_f32 v[62:63], v[62:63], v[64:65]
	v_pk_add_f32 v[58:59], v[58:59], v[60:61]
	s_nop 0
	v_pk_add_f32 v[58:59], v[62:63], v[58:59]
	s_nop 0
	v_add_f32_e32 v37, v58, v59
	ds_bpermute_b32 v58, v17, v37
	s_waitcnt lgkmcnt(0)
; #define GAS __attribute__((address_space(1)))
; DI unsigned pk2(float lo, float hi) { f32x2 v = {lo, hi}; bf16x2_t b = __builtin_convertvector(v, bf16x2_t); return __builtin_bit_cast(unsigned, b); }
; DI float bf_lo(unsigned u) { return __uint_as_float(u << 16); }
; DI float bf_hi(unsigned u) { return __uint_as_float(u & 0xffff0000u); }
; DI void norm_row_bf16(const f32x4 (&v)[4], const float* g, bf16_t* orow, int lane) {
;     float s = 0.f;
; #pragma unroll
;     for (int j = 0; j < 4; ++j) s += (v[j].x * v[j].x + v[j].y * v[j].y) + (v[j].z * v[j].z + v[j].w * v[j].w);
;     const float rstd = __builtin_amdgcn_rsqf(wave_sum(s, lane) * (1.0f / DM) + RMS_EPS);
;     GAS u32x2* o8 = (GAS u32x2*)orow + lane;
; #pragma unroll
;     for (int j = 0; j < 4; ++j) { const f32x4 gg = ((const GAS f32x4*)g)[lane + 64 * j]; u32x2 w; w.x = pk2(v[j].x * rstd * gg.x, v[j].y * rstd * gg.y); w.y = pk2(v[j].z * rstd * gg.z, v[j].w * rstd * gg.w); o8[64 * j] = w; }
; }
; DI void post_pass(int wv, const bf16_t* raw, long raw_row0, float* x, const float* gpost, const float* gpre, bf16_t* XN, int row_lo, int row_hi, const float* xin_p = nullptr, const float* xin_s = nullptr) {
;     ...
;         for (int q = 0; q < 2; ++q) { const int rw = row + q * NGW;
;             const GAS u32x2* rr = (const GAS u32x2*)(raw + (size_t)(rw - raw_row0) * DM) + lane;
;             const GAS f32x4* xr = (const GAS f32x4*)(xin_p ? (rw < TOK_P ? xin_p + (size_t)rw * DM : xin_s + (size_t)(rw - TOK_P) * DM) : x + (size_t)rw * DM) + lane;
; #pragma unroll
;             for (int j = 0; j < 4; ++j) { const u32x2 w = rr[64 * j]; v[q][j] = (f32x4){bf_lo(w.x), bf_hi(w.x), bf_lo(w.y), bf_hi(w.y)}; xv[q][j] = xr[64 * j]; } }
; #pragma unroll
;         for (int q = 0; q < 2; ++q)
; #pragma unroll
;             for (int j = 0; j < 4; ++j) s[q] += (v[q][j].x * v[q][j].x + v[q][j].y * v[q][j].y) + (v[q][j].z * v[q][j].z + v[q][j].w * v[q][j].w);
; #pragma unroll
;         for (int q = 0; q < 2; ++q) { const int rw = row + q * NGW; GAS f32x4* xr = (GAS f32x4*)(x + (size_t)rw * DM) + lane;
;             const float rstd = __builtin_amdgcn_rsqf(wave_sum(s[q], lane) * (1.0f / DM) + RMS_EPS);
	v_add_f32_e32 v37, v37, v58
	ds_bpermute_b32 v58, v30, v37
	s_waitcnt lgkmcnt(0)
	v_add_f32_e32 v37, v37, v58
	ds_bpermute_b32 v58, v31, v37
	s_waitcnt lgkmcnt(0)
	v_add_f32_e32 v37, v37, v58
	ds_bpermute_b32 v58, v32, v37
	s_waitcnt lgkmcnt(0)
	v_add_f32_e32 v37, v37, v58
	ds_bpermute_b32 v58, v33, v37
	s_waitcnt lgkmcnt(0)
	v_add_f32_e32 v37, v37, v58
	ds_bpermute_b32 v58, v34, v37
	s_waitcnt lgkmcnt(0)
	v_add_f32_e32 v37, v37, v58
	v_fmamk_f32 v37, v37, 0x3a800000, v174
	v_rsq_f32_e32 v58, v37
	s_nop 0
	v_pk_mul_f32 v[38:39], v[38:39], v[58:59] op_sel_hi:[1,0]
	v_pk_mul_f32 v[40:41], v[40:41], v[58:59] op_sel_hi:[1,0]
	v_pk_mul_f32 v[46:47], v[46:47], v[58:59] op_sel_hi:[1,0]
	v_pk_mul_f32 v[48:49], v[48:49], v[58:59] op_sel_hi:[1,0]
	v_pk_mul_f32 v[42:43], v[42:43], v[58:59] op_sel_hi:[1,0]
	v_pk_mul_f32 v[44:45], v[44:45], v[58:59] op_sel_hi:[1,0]
	s_waitcnt vmcnt(0)
	v_pk_mul_f32 v[38:39], v[54:55], v[38:39]
	v_pk_mul_f32 v[40:41], v[56:57], v[40:41]
	v_cvt_pk_bf16_f32 v38, v38, v39
	v_cvt_pk_bf16_f32 v39, v40, v41
	global_store_dwordx2 v35, v[38:39], s[10:11]
	global_load_dwordx4 v[38:41], v[18:19], off offset:1024
	v_lshlrev_b32_e32 v54, 16, v23
	v_and_b32_e32 v55, 0xffff0000, v23
	v_mul_f32_e32 v56, v55, v55
	v_pk_fma_f32 v[56:57], v[54:55], v[54:55], v[56:57] op_sel_hi:[1,1,0]
	s_waitcnt vmcnt(0)
	v_pk_mul_f32 v[38:39], v[38:39], v[46:47]
	v_pk_mul_f32 v[40:41], v[40:41], v[48:49]
	v_cvt_pk_bf16_f32 v38, v38, v39
	v_cvt_pk_bf16_f32 v39, v40, v41
	global_store_dwordx2 v35, v[38:39], s[10:11] offset:512
	global_load_dwordx4 v[38:41], v[18:19], off offset:2048
	v_pk_mul_f32 v[48:49], v[50:51], v[58:59] op_sel_hi:[1,0]
	v_pk_mul_f32 v[50:51], v[52:53], v[58:59] op_sel_hi:[1,0]
	v_lshlrev_b32_e32 v46, 16, v26
	v_and_b32_e32 v47, 0xffff0000, v26
	v_lshlrev_b32_e32 v26, 16, v27
	v_and_b32_e32 v27, 0xffff0000, v27
	v_lshlrev_b32_e32 v52, 16, v22
	v_and_b32_e32 v53, 0xffff0000, v22
	v_mul_f32_e32 v22, v27, v27
	s_waitcnt vmcnt(0)
	v_pk_mul_f32 v[38:39], v[38:39], v[42:43]
	v_pk_mul_f32 v[40:41], v[40:41], v[44:45]
	v_cvt_pk_bf16_f32 v38, v38, v39
	v_cvt_pk_bf16_f32 v39, v40, v41
	global_store_dwordx2 v35, v[38:39], s[10:11] offset:1024
	global_load_dwordx4 v[38:41], v[18:19], off offset:3072
	v_lshlrev_b32_e32 v43, 16, v28
	v_mul_f32_e32 v42, v47, v47
	v_mov_b32_e32 v23, v43
	v_pk_fma_f32 v[58:59], v[26:27], v[26:27], v[22:23] op_sel_hi:[1,1,0]
	v_pk_fma_f32 v[60:61], v[46:47], v[46:47], v[42:43] op_sel_hi:[1,1,0]
	v_and_b32_e32 v45, 0xffff0000, v28
	v_lshlrev_b32_e32 v28, 16, v29
	v_and_b32_e32 v29, 0xffff0000, v29
	v_mul_f32_e32 v44, v53, v53
	v_mov_b32_e32 v42, v60
	v_mov_b32_e32 v22, v58
	v_mul_f32_e32 v37, v45, v45
	v_mul_f32_e32 v64, v28, v28
	v_mul_f32_e32 v65, v29, v29
	v_pk_fma_f32 v[62:63], v[52:53], v[52:53], v[44:45] op_sel_hi:[1,1,0]
	v_pk_add_f32 v[58:59], v[60:61], v[58:59]
	v_pk_mul_f32 v[22:23], v[42:43], v[22:23]
	v_mov_b32_e32 v63, v64
	v_mov_b32_e32 v57, v65
	v_mov_b32_e32 v59, v23
	v_pk_add_f32 v[56:57], v[62:63], v[56:57]
	v_mov_b32_e32 v44, v43
	s_waitcnt vmcnt(0)
	v_pk_mul_f32 v[38:39], v[38:39], v[48:49]
	v_pk_mul_f32 v[40:41], v[40:41], v[50:51]
	v_cvt_pk_bf16_f32 v38, v38, v39
	v_cvt_pk_bf16_f32 v39, v40, v41
	global_store_dwordx2 v35, v[38:39], s[10:11] offset:1536
	global_load_dwordx4 v[38:41], v[20:21], off
	v_and_b32_e32 v51, 0xffff0000, v25
	v_and_b32_e32 v50, 0xffff0000, v24
	v_lshlrev_b32_e32 v49, 16, v25
	v_lshlrev_b32_e32 v48, 16, v24
	v_pk_mul_f32 v[24:25], v[50:51], v[50:51]
	s_nop 0
	v_pk_fma_f32 v[24:25], v[48:49], v[48:49], v[24:25]
	s_nop 0
	v_pk_add_f32 v[24:25], v[24:25], v[24:25] op_sel:[0,1] op_sel_hi:[1,0]
	s_nop 0
	v_mov_b32_e32 v25, v37
	v_pk_add_f32 v[22:23], v[58:59], v[24:25]
	s_nop 0
	v_pk_add_f32 v[22:23], v[22:23], v[56:57]
	s_nop 0
	v_add_f32_e32 v22, v22, v23
	ds_bpermute_b32 v23, v17, v22
	s_waitcnt lgkmcnt(0)
	v_add_f32_e32 v22, v22, v23
	ds_bpermute_b32 v23, v30, v22
	s_waitcnt lgkmcnt(0)
	v_add_f32_e32 v22, v22, v23
	ds_bpermute_b32 v23, v31, v22
	s_waitcnt lgkmcnt(0)
	v_add_f32_e32 v22, v22, v23
	ds_bpermute_b32 v23, v32, v22
	s_waitcnt lgkmcnt(0)
	v_add_f32_e32 v22, v22, v23
	ds_bpermute_b32 v23, v33, v22
	s_waitcnt lgkmcnt(0)
	v_add_f32_e32 v22, v22, v23
	ds_bpermute_b32 v23, v34, v22
	s_waitcnt lgkmcnt(0)
; #define GAS __attribute__((address_space(1)))
; DI unsigned pk2(float lo, float hi) { f32x2 v = {lo, hi}; bf16x2_t b = __builtin_convertvector(v, bf16x2_t); return __builtin_bit_cast(unsigned, b); }
; DI void norm_row_bf16(const f32x4 (&v)[4], const float* g, bf16_t* orow, int lane) {
;     float s = 0.f;
; #pragma unroll
;     for (int j = 0; j < 4; ++j) s += (v[j].x * v[j].x + v[j].y * v[j].y) + (v[j].z * v[j].z + v[j].w * v[j].w);
;     const float rstd = __builtin_amdgcn_rsqf(wave_sum(s, lane) * (1.0f / DM) + RMS_EPS);
;     GAS u32x2* o8 = (GAS u32x2*)orow + lane;
; #pragma unroll
;     for (int j = 0; j < 4; ++j) { const f32x4 gg = ((const GAS f32x4*)g)[lane + 64 * j]; u32x2 w; w.x = pk2(v[j].x * rstd * gg.x, v[j].y * rstd * gg.y); w.y = pk2(v[j].z * rstd * gg.z, v[j].w * rstd * gg.w); o8[64 * j] = w; }
; }
; DI void post_pass(int wv, const bf16_t* raw, long raw_row0, float* x, const float* gpost, const float* gpre, bf16_t* XN, int row_lo, int row_hi, const float* xin_p = nullptr, const float* xin_s = nullptr) {
;     ...
;         for (int q = 0; q < 2; ++q) { const int rw = row + q * NGW; GAS f32x4* xr = (GAS f32x4*)(x + (size_t)rw * DM) + lane;
;             const float rstd = __builtin_amdgcn_rsqf(wave_sum(s[q], lane) * (1.0f / DM) + RMS_EPS);
; #pragma unroll
;             for (int j = 0; j < 4; ++j) { const f32x4 gg = ((const GAS f32x4*)gpost)[lane + 64 * j]; xv[q][j] = xv[q][j] + v[q][j] * rstd * gg; xr[64 * j] = xv[q][j]; }
;             if (gpre) norm_row_bf16(xv[q], gpre, XN + (size_t)rw * DM, lane); }
	v_add_f32_e32 v22, v22, v23
	v_fmamk_f32 v22, v22, 0x3a800000, v174
	v_rsq_f32_e32 v42, v22
	s_nop 0
	v_pk_mul_f32 v[22:23], v[42:43], v[26:27] op_sel_hi:[0,1]
	v_pk_mul_f32 v[24:25], v[42:43], v[46:47] op_sel_hi:[0,1]
	v_mov_b32_e32 v26, v49
	v_mov_b32_e32 v27, v51
	v_mov_b32_e32 v49, v50
	v_pk_mul_f32 v[26:27], v[42:43], v[26:27] op_sel_hi:[0,1]
	v_pk_mul_f32 v[28:29], v[42:43], v[28:29] op_sel_hi:[0,1]
	s_waitcnt vmcnt(0)
	v_pk_fma_f32 v[0:1], v[38:39], v[24:25], v[0:1]
	v_pk_fma_f32 v[2:3], v[40:41], v[22:23], v[2:3]
	global_store_dwordx4 v36, v[0:3], s[12:13]
	global_load_dwordx4 v[22:25], v[20:21], off offset:1024
	v_pk_mul_f32 v[38:39], v[42:43], v[48:49] op_sel_hi:[0,1]
	s_waitcnt vmcnt(0)
	v_pk_fma_f32 v[4:5], v[22:23], v[38:39], v[4:5]
	v_pk_fma_f32 v[6:7], v[24:25], v[26:27], v[6:7]
	global_store_dwordx4 v36, v[4:7], s[12:13] offset:1024
	global_load_dwordx4 v[22:25], v[20:21], off offset:2048
	v_pk_mul_f32 v[26:27], v[42:43], v[54:55] op_sel_hi:[0,1]
	v_pk_mul_f32 v[38:39], v[42:43], v[52:53] op_sel_hi:[0,1]
	s_waitcnt vmcnt(0)
	v_pk_fma_f32 v[8:9], v[22:23], v[38:39], v[8:9]
	v_pk_fma_f32 v[10:11], v[24:25], v[26:27], v[10:11]
	global_store_dwordx4 v36, v[8:11], s[12:13] offset:2048
	global_load_dwordx4 v[22:25], v[20:21], off offset:3072
	v_pk_mul_f32 v[26:27], v[42:43], v[44:45] op_sel_hi:[0,1]
	s_waitcnt vmcnt(0)
	v_pk_fma_f32 v[14:15], v[24:25], v[28:29], v[14:15]
	v_pk_fma_f32 v[12:13], v[22:23], v[26:27], v[12:13]
	global_store_dwordx4 v36, v[12:15], s[12:13] offset:3072
	global_load_dwordx4 v[22:25], v[18:19], off
	v_pk_mul_f32 v[26:27], v[0:1], v[0:1]
	v_pk_mul_f32 v[28:29], v[2:3], v[2:3]
	s_nop 0
	v_pk_mov_b32 v[36:37], v[26:27], v[28:29] op_sel:[1,0]
	v_mov_b32_e32 v27, v29
	v_pk_add_f32 v[26:27], v[36:37], v[26:27]
	v_pk_mul_f32 v[28:29], v[4:5], v[4:5]
	v_pk_mul_f32 v[36:37], v[6:7], v[6:7]
	v_pk_add_f32 v[26:27], v[26:27], v[26:27] op_sel_hi:[0,1]
	v_pk_mov_b32 v[38:39], v[28:29], v[36:37] op_sel:[1,0]
	v_mov_b32_e32 v29, v37
	v_pk_add_f32 v[28:29], v[38:39], v[28:29]
	v_mul_f32_e32 v26, v8, v8
	v_pk_add_f32 v[28:29], v[28:29], v[28:29] op_sel_hi:[0,1]
	v_mul_f32_e32 v28, v10, v10
	v_pk_fma_f32 v[36:37], v[8:9], v[8:9], v[26:27] op_sel_hi:[1,1,0]
	v_pk_fma_f32 v[38:39], v[10:11], v[10:11], v[28:29] op_sel_hi:[1,1,0]
	v_mul_f32_e32 v36, v12, v12
	v_mul_f32_e32 v38, v13, v13
	v_mul_f32_e32 v26, v14, v14
	v_mul_f32_e32 v28, v15, v15
	v_pk_add_f32 v[36:37], v[36:37], v[38:39]
	v_pk_add_f32 v[26:27], v[26:27], v[28:29]
	s_nop 0
	v_pk_add_f32 v[26:27], v[36:37], v[26:27]
	s_nop 0
	v_add_f32_e32 v26, v26, v27
	ds_bpermute_b32 v27, v17, v26
	s_waitcnt lgkmcnt(0)
	v_add_f32_e32 v26, v26, v27
	ds_bpermute_b32 v27, v30, v26
	s_waitcnt lgkmcnt(0)
	v_add_f32_e32 v26, v26, v27
	ds_bpermute_b32 v27, v31, v26
	s_waitcnt lgkmcnt(0)
	v_add_f32_e32 v26, v26, v27
	ds_bpermute_b32 v27, v32, v26
	s_waitcnt lgkmcnt(0)
	v_add_f32_e32 v26, v26, v27
	ds_bpermute_b32 v27, v33, v26
	s_waitcnt lgkmcnt(0)
	v_add_f32_e32 v26, v26, v27
	ds_bpermute_b32 v27, v34, v26
	s_waitcnt lgkmcnt(0)
	v_add_f32_e32 v26, v26, v27
	v_fmamk_f32 v26, v26, 0x3a800000, v174
	v_rsq_f32_e32 v26, v26
	s_nop 0
	v_pk_mul_f32 v[0:1], v[0:1], v[26:27] op_sel_hi:[1,0]
	v_pk_mul_f32 v[2:3], v[2:3], v[26:27] op_sel_hi:[1,0]
	v_pk_mul_f32 v[4:5], v[4:5], v[26:27] op_sel_hi:[1,0]
	v_pk_mul_f32 v[6:7], v[6:7], v[26:27] op_sel_hi:[1,0]
	s_waitcnt vmcnt(0)
	v_pk_mul_f32 v[0:1], v[22:23], v[0:1]
	v_pk_mul_f32 v[2:3], v[24:25], v[2:3]
	v_cvt_pk_bf16_f32 v0, v0, v1
	v_cvt_pk_bf16_f32 v1, v2, v3
	global_store_dwordx2 v35, v[0:1], s[8:9]
	global_load_dwordx4 v[0:3], v[18:19], off offset:1024
	s_waitcnt vmcnt(0)
	v_pk_mul_f32 v[0:1], v[0:1], v[4:5]
	v_pk_mul_f32 v[2:3], v[2:3], v[6:7]
	v_cvt_pk_bf16_f32 v0, v0, v1
	v_cvt_pk_bf16_f32 v1, v2, v3
	global_store_dwordx2 v35, v[0:1], s[8:9] offset:512
	global_load_dwordx4 v[0:3], v[18:19], off offset:2048
	v_pk_mul_f32 v[4:5], v[8:9], v[26:27] op_sel_hi:[1,0]
	v_pk_mul_f32 v[6:7], v[10:11], v[26:27] op_sel_hi:[1,0]
	s_waitcnt vmcnt(0)
	v_pk_mul_f32 v[0:1], v[0:1], v[4:5]
	v_pk_mul_f32 v[2:3], v[2:3], v[6:7]
	v_cvt_pk_bf16_f32 v0, v0, v1
	v_cvt_pk_bf16_f32 v1, v2, v3
	global_store_dwordx2 v35, v[0:1], s[8:9] offset:1024
	global_load_dwordx4 v[0:3], v[18:19], off offset:3072
	v_pk_mul_f32 v[4:5], v[12:13], v[26:27] op_sel_hi:[1,0]
	v_pk_mul_f32 v[6:7], v[14:15], v[26:27] op_sel_hi:[1,0]
	s_waitcnt vmcnt(0)
	v_pk_mul_f32 v[0:1], v[0:1], v[4:5]
	v_pk_mul_f32 v[2:3], v[2:3], v[6:7]
	v_cvt_pk_bf16_f32 v0, v0, v1
	v_cvt_pk_bf16_f32 v1, v2, v3
	global_store_dwordx2 v35, v[0:1], s[8:9] offset:1536
	s_cbranch_scc1 .LBB0_519

; #define GAS __attribute__((address_space(1)))
; DI float bf_lo(unsigned u) { return __uint_as_float(u << 16); }
; DI float bf_hi(unsigned u) { return __uint_as_float(u & 0xffff0000u); }
; DI void post_pass(int wv, const bf16_t* raw, long raw_row0, float* x, const float* gpost, const float* gpre, bf16_t* XN, int row_lo, int row_hi, const float* xin_p = nullptr, const float* xin_s = nullptr) {
;     ...
;     for (int row = row_lo + gw; row < row_hi; row += 2 * NGW) {
;         f32x4 v[2][4], xv[2][4]; float s[2] = {0.f, 0.f};
; #pragma unroll
;         for (int q = 0; q < 2; ++q) { const int rw = row + q * NGW;
;             const GAS u32x2* rr = (const GAS u32x2*)(raw + (size_t)(rw - raw_row0) * DM) + lane;
;             const GAS f32x4* xr = (const GAS f32x4*)(xin_p ? (rw < TOK_P ? xin_p + (size_t)rw * DM : xin_s + (size_t)(rw - TOK_P) * DM) : x + (size_t)rw * DM) + lane;
; #pragma unroll
;             for (int j = 0; j < 4; ++j) { const u32x2 w = rr[64 * j]; v[q][j] = (f32x4){bf_lo(w.x), bf_hi(w.x), bf_lo(w.y), bf_hi(w.y)}; xv[q][j] = xr[64 * j]; } }
; #pragma unroll
;         for (int q = 0; q < 2; ++q)
; #pragma unroll
;             for (int j = 0; j < 4; ++j) s[q] += (v[q][j].x * v[q][j].x + v[q][j].y * v[q][j].y) + (v[q][j].z * v[q][j].z + v[q][j].w * v[q][j].w);
; #pragma unroll
;         for (int q = 0; q < 2; ++q) { const int rw = row + q * NGW; GAS f32x4* xr = (GAS f32x4*)(x + (size_t)rw * DM) + lane;
;             const float rstd = __builtin_amdgcn_rsqf(wave_sum(s[q], lane) * (1.0f / DM) + RMS_EPS);
; #pragma unroll
;             for (int j = 0; j < 4; ++j) { const f32x4 gg = ((const GAS f32x4*)gpost)[lane + 64 * j]; xv[q][j] = xv[q][j] + v[q][j] * rstd * gg; xr[64 * j] = xv[q][j]; }
.LBB0_525:
	s_ashr_i32 s17, s16, 31
	s_lshl_b64 s[6:7], s[16:17], 11
	s_add_u32 s6, s22, s6
	s_addc_u32 s7, s23, s7
	v_lshlrev_b32_e32 v57, 3, v32
	global_load_dwordx2 v[0:1], v57, s[6:7] offset:1536 nt
	global_load_dwordx2 v[2:3], v57, s[6:7] nt
	global_load_dwordx2 v[4:5], v57, s[6:7] offset:512 nt
	global_load_dwordx2 v[6:7], v57, s[6:7] offset:1024 nt
	s_add_i32 s26, s16, 0xffffc000
	s_cmpk_lt_i32 s16, 0x4000
	s_cselect_b64 s[6:7], -1, 0
	s_and_b64 s[14:15], s[6:7], exec
	s_cselect_b32 s27, s8, s21
	s_cselect_b32 s28, s9, s20
	s_or_b64 s[6:7], s[10:11], s[6:7]
	s_and_b64 s[6:7], s[6:7], exec
	s_cselect_b32 s7, s17, 0
	s_cselect_b32 s6, s16, s26
	s_and_b64 s[14:15], s[10:11], exec
	global_load_dwordx4 v[16:19], v[36:37], off
	s_cselect_b32 s14, s18, s28
	s_cselect_b32 s15, s19, s27
	s_lshl_b64 s[6:7], s[6:7], 12
	s_add_u32 s6, s15, s6
	v_lshlrev_b32_e32 v58, 4, v32
	s_addc_u32 s7, s14, s7
	global_load_dwordx4 v[24:27], v58, s[6:7]
	global_load_dwordx4 v[60:63], v58, s[6:7] offset:1024
	global_load_dwordx4 v[64:67], v58, s[6:7] offset:2048
	global_load_dwordx4 v[20:23], v58, s[6:7] offset:3072
	s_add_i32 s14, s16, s72
	s_ashr_i32 s15, s14, 31
	s_lshl_b64 s[6:7], s[14:15], 11
	s_add_u32 s6, s22, s6
	s_addc_u32 s7, s23, s7
	s_add_i32 s28, s14, 0xffffc000
	s_cmpk_lt_i32 s14, 0x4000
	global_load_dwordx2 v[44:45], v57, s[6:7] nt
	global_load_dwordx2 v[42:43], v57, s[6:7] offset:512 nt
	global_load_dwordx2 v[40:41], v57, s[6:7] offset:1024 nt
	global_load_dwordx2 v[38:39], v57, s[6:7] offset:1536 nt
	s_cselect_b64 s[6:7], -1, 0
	s_and_b64 s[26:27], s[6:7], exec
	s_cselect_b32 s29, s8, s21
	s_cselect_b32 s30, s9, s20
	s_or_b64 s[6:7], s[10:11], s[6:7]
	s_and_b64 s[6:7], s[6:7], exec
	s_cselect_b32 s7, s15, 0
	s_cselect_b32 s6, s14, s28
	s_and_b64 s[26:27], s[10:11], exec
	s_cselect_b32 s26, s18, s30
	s_cselect_b32 s27, s19, s29
	s_lshl_b64 s[6:7], s[6:7], 12
	s_add_u32 s6, s27, s6
	s_addc_u32 s7, s26, s7
	s_lshl_b64 s[26:27], s[16:17], 12
	s_add_u32 s26, s19, s26
	s_addc_u32 s27, s18, s27
	v_cndmask_b32_e64 v46, 0, 1, s[12:13]
	s_andn2_b64 vcc, exec, s[12:13]
	s_waitcnt vmcnt(0)
	v_lshlrev_b32_e32 v49, 16, v0
	v_and_b32_e32 v29, 0xffff0000, v2
	v_and_b32_e32 v31, 0xffff0000, v3
	v_and_b32_e32 v47, 0xffff0000, v0
	v_lshlrev_b32_e32 v50, 16, v1
	v_and_b32_e32 v51, 0xffff0000, v1
	v_lshlrev_b32_e32 v28, 16, v2
	v_lshlrev_b32_e32 v30, 16, v3
	v_lshlrev_b32_e32 v68, 16, v4
	v_and_b32_e32 v71, 0xffff0000, v5
	v_and_b32_e32 v70, 0xffff0000, v4
	v_mul_f32_e32 v0, v31, v31
	v_mul_f32_e32 v4, v29, v29
	v_mov_b32_e32 v1, v49
	v_lshlrev_b32_e32 v69, 16, v5
	v_and_b32_e32 v73, 0xffff0000, v6
	v_and_b32_e32 v75, 0xffff0000, v7
	v_pk_mul_f32 v[2:3], v[70:71], v[70:71]
	v_pk_fma_f32 v[10:11], v[30:31], v[30:31], v[0:1] op_sel_hi:[1,1,0]
	v_pk_fma_f32 v[4:5], v[28:29], v[28:29], v[4:5] op_sel_hi:[1,1,0]
	v_lshlrev_b32_e32 v72, 16, v6
	v_lshlrev_b32_e32 v74, 16, v7
	v_mul_f32_e32 v6, v73, v73
	v_mul_f32_e32 v8, v75, v75
	v_pk_fma_f32 v[2:3], v[68:69], v[68:69], v[2:3]
	v_mov_b32_e32 v48, v4
	v_mov_b32_e32 v0, v10
	v_mul_f32_e32 v12, v47, v47
	v_mul_f32_e32 v13, v50, v50
	v_mul_f32_e32 v14, v51, v51
	v_pk_fma_f32 v[6:7], v[72:73], v[72:73], v[6:7] op_sel_hi:[1,1,0]
	v_pk_fma_f32 v[8:9], v[74:75], v[74:75], v[8:9] op_sel_hi:[1,1,0]
	v_pk_add_f32 v[4:5], v[4:5], v[10:11]
	v_pk_add_f32 v[2:3], v[2:3], v[2:3] op_sel:[0,1] op_sel_hi:[1,0]
	v_pk_mul_f32 v[0:1], v[48:49], v[0:1]
	v_mov_b32_e32 v7, v13
	v_mov_b32_e32 v9, v14
	v_mov_b32_e32 v3, v12
	v_mov_b32_e32 v5, v1
	v_pk_add_f32 v[6:7], v[6:7], v[8:9]
	v_pk_add_f32 v[0:1], v[4:5], v[2:3]
	global_load_dwordx4 v[12:15], v58, s[6:7]
	global_load_dwordx4 v[8:11], v58, s[6:7] offset:1024
	v_pk_add_f32 v[0:1], v[0:1], v[6:7]
	s_nop 0
	v_add_f32_e32 v0, v0, v1
	ds_bpermute_b32 v1, v33, v0
	s_waitcnt lgkmcnt(0)
	v_add_f32_e32 v0, v0, v1
	ds_bpermute_b32 v1, v52, v0
	s_waitcnt lgkmcnt(0)
	v_add_f32_e32 v0, v0, v1
	ds_bpermute_b32 v1, v53, v0
	s_waitcnt lgkmcnt(0)
	v_add_f32_e32 v0, v0, v1
	ds_bpermute_b32 v1, v54, v0
	s_waitcnt lgkmcnt(0)
	v_add_f32_e32 v0, v0, v1
	ds_bpermute_b32 v1, v55, v0
	s_waitcnt lgkmcnt(0)
	v_add_f32_e32 v0, v0, v1
	ds_bpermute_b32 v1, v56, v0
	s_waitcnt lgkmcnt(0)
	v_add_f32_e32 v0, v0, v1
	v_fmamk_f32 v0, v0, 0x3a800000, v174
	v_rsq_f32_e32 v48, v0
	global_load_dwordx4 v[4:7], v58, s[6:7] offset:2048
	global_load_dwordx4 v[0:3], v58, s[6:7] offset:3072
	v_cmp_ne_u32_e64 s[6:7], 1, v46
	v_mov_b32_e32 v46, v49
	v_pk_mul_f32 v[28:29], v[48:49], v[28:29] op_sel_hi:[0,1]
	v_pk_mul_f32 v[30:31], v[48:49], v[30:31] op_sel_hi:[0,1]
	v_pk_fma_f32 v[30:31], v[18:19], v[30:31], v[26:27]
	v_pk_fma_f32 v[28:29], v[16:17], v[28:29], v[24:25]
	global_store_dwordx4 v58, v[28:31], s[26:27]
	global_load_dwordx4 v[16:19], v[36:37], off offset:1024
	v_mov_b32_e32 v24, v69
	v_mov_b32_e32 v25, v71
	v_mov_b32_e32 v69, v70
	v_pk_mul_f32 v[26:27], v[48:49], v[24:25] op_sel_hi:[0,1]
	v_pk_mul_f32 v[24:25], v[48:49], v[68:69] op_sel_hi:[0,1]
	v_pk_mul_f32 v[50:51], v[48:49], v[50:51] op_sel_hi:[0,1]
	v_pk_mul_f32 v[46:47], v[48:49], v[46:47] op_sel_hi:[0,1]
	s_waitcnt vmcnt(0)
	v_pk_fma_f32 v[24:25], v[16:17], v[24:25], v[60:61]
	v_pk_fma_f32 v[26:27], v[18:19], v[26:27], v[62:63]
	global_store_dwordx4 v58, v[24:27], s[26:27] offset:1024
	global_load_dwordx4 v[16:19], v[36:37], off offset:2048
	v_pk_mul_f32 v[60:61], v[48:49], v[74:75] op_sel_hi:[0,1]
	v_pk_mul_f32 v[62:63], v[48:49], v[72:73] op_sel_hi:[0,1]
	s_waitcnt vmcnt(0)
	v_pk_fma_f32 v[16:17], v[16:17], v[62:63], v[64:65]
	v_pk_fma_f32 v[18:19], v[18:19], v[60:61], v[66:67]
	global_store_dwordx4 v58, v[16:19], s[26:27] offset:2048
	global_load_dwordx4 v[60:63], v[36:37], off offset:3072
	s_waitcnt vmcnt(0)
	v_pk_fma_f32 v[20:21], v[60:61], v[46:47], v[20:21]
	v_pk_fma_f32 v[22:23], v[62:63], v[50:51], v[22:23]
	global_store_dwordx4 v58, v[20:23], s[26:27] offset:3072
	s_cbranch_vccnz .LBB0_527
; #define GAS __attribute__((address_space(1)))
; DI unsigned pk2(float lo, float hi) { f32x2 v = {lo, hi}; bf16x2_t b = __builtin_convertvector(v, bf16x2_t); return __builtin_bit_cast(unsigned, b); }
; DI void norm_row_bf16(const f32x4 (&v)[4], const float* g, bf16_t* orow, int lane) {
;     float s = 0.f;
; #pragma unroll
;     for (int j = 0; j < 4; ++j) s += (v[j].x * v[j].x + v[j].y * v[j].y) + (v[j].z * v[j].z + v[j].w * v[j].w);
;     const float rstd = __builtin_amdgcn_rsqf(wave_sum(s, lane) * (1.0f / DM) + RMS_EPS);
;     GAS u32x2* o8 = (GAS u32x2*)orow + lane;
; #pragma unroll
;     for (int j = 0; j < 4; ++j) { const f32x4 gg = ((const GAS f32x4*)g)[lane + 64 * j]; u32x2 w; w.x = pk2(v[j].x * rstd * gg.x, v[j].y * rstd * gg.y); w.y = pk2(v[j].z * rstd * gg.z, v[j].w * rstd * gg.w); o8[64 * j] = w; }
; }
	v_pk_mul_f32 v[46:47], v[30:31], v[30:31]
	v_pk_mul_f32 v[48:49], v[28:29], v[28:29]
	s_lshl_b64 s[16:17], s[16:17], 10
	v_pk_mov_b32 v[50:51], v[48:49], v[46:47] op_sel:[1,0]
	v_mov_b32_e32 v49, v47
	v_pk_add_f32 v[46:47], v[50:51], v[48:49]
	v_pk_mul_f32 v[48:49], v[26:27], v[26:27]
	v_pk_add_f32 v[46:47], v[46:47], v[46:47] op_sel_hi:[0,1]
	v_pk_mul_f32 v[50:51], v[24:25], v[24:25]
	v_mul_f32_e32 v46, v16, v16
	v_pk_mov_b32 v[60:61], v[50:51], v[48:49] op_sel:[1,0]
	v_mov_b32_e32 v51, v49
	v_pk_add_f32 v[48:49], v[60:61], v[50:51]
	v_pk_fma_f32 v[50:51], v[16:17], v[16:17], v[46:47] op_sel_hi:[1,1,0]
	v_mul_f32_e32 v46, v18, v18
	v_pk_add_f32 v[48:49], v[48:49], v[48:49] op_sel_hi:[0,1]
	v_pk_fma_f32 v[60:61], v[18:19], v[18:19], v[46:47] op_sel_hi:[1,1,0]
	v_mul_f32_e32 v50, v20, v20
	v_mul_f32_e32 v60, v21, v21
	v_mul_f32_e32 v46, v22, v22
	v_mul_f32_e32 v48, v23, v23
	v_pk_add_f32 v[50:51], v[50:51], v[60:61]
	v_pk_add_f32 v[46:47], v[46:47], v[48:49]
	s_lshl_b64 s[16:17], s[16:17], 1
	v_pk_add_f32 v[46:47], v[50:51], v[46:47]
	global_load_dwordx4 v[48:51], v[34:35], off
	v_add_f32_e32 v46, v46, v47
	ds_bpermute_b32 v47, v33, v46
	s_add_u32 s16, s24, s16
	s_addc_u32 s17, s25, s17
	s_waitcnt lgkmcnt(0)
	v_add_f32_e32 v46, v46, v47
	ds_bpermute_b32 v47, v52, v46
	s_waitcnt lgkmcnt(0)
	v_add_f32_e32 v46, v46, v47
	ds_bpermute_b32 v47, v53, v46
	s_waitcnt lgkmcnt(0)
	v_add_f32_e32 v46, v46, v47
	ds_bpermute_b32 v47, v54, v46
	s_waitcnt lgkmcnt(0)
	v_add_f32_e32 v46, v46, v47
	ds_bpermute_b32 v47, v55, v46
	s_waitcnt lgkmcnt(0)
	v_add_f32_e32 v46, v46, v47
	ds_bpermute_b32 v47, v56, v46
	s_waitcnt lgkmcnt(0)
	v_add_f32_e32 v46, v46, v47
	v_fmamk_f32 v46, v46, 0x3a800000, v174
	v_rsq_f32_e32 v46, v46
	s_nop 0
	v_pk_mul_f32 v[28:29], v[28:29], v[46:47] op_sel_hi:[1,0]
	v_pk_mul_f32 v[30:31], v[30:31], v[46:47] op_sel_hi:[1,0]
	v_pk_mul_f32 v[24:25], v[24:25], v[46:47] op_sel_hi:[1,0]
	v_pk_mul_f32 v[26:27], v[26:27], v[46:47] op_sel_hi:[1,0]
	v_pk_mul_f32 v[16:17], v[16:17], v[46:47] op_sel_hi:[1,0]
	v_pk_mul_f32 v[18:19], v[18:19], v[46:47] op_sel_hi:[1,0]
	v_pk_mul_f32 v[20:21], v[20:21], v[46:47] op_sel_hi:[1,0]
	s_waitcnt vmcnt(0)
	v_pk_mul_f32 v[28:29], v[48:49], v[28:29]
	v_pk_mul_f32 v[30:31], v[50:51], v[30:31]
	v_cvt_pk_bf16_f32 v28, v28, v29
	v_cvt_pk_bf16_f32 v29, v30, v31
	global_store_dwordx2 v57, v[28:29], s[16:17]
	global_load_dwordx4 v[28:31], v[34:35], off offset:1024
	s_waitcnt vmcnt(0)
	v_pk_mul_f32 v[24:25], v[28:29], v[24:25]
	v_pk_mul_f32 v[26:27], v[30:31], v[26:27]
	v_cvt_pk_bf16_f32 v24, v24, v25
	v_cvt_pk_bf16_f32 v25, v26, v27
	global_store_dwordx2 v57, v[24:25], s[16:17] offset:512
	global_load_dwordx4 v[24:27], v[34:35], off offset:2048
	s_waitcnt vmcnt(0)
	v_pk_mul_f32 v[16:17], v[24:25], v[16:17]
	v_pk_mul_f32 v[18:19], v[26:27], v[18:19]
	v_cvt_pk_bf16_f32 v16, v16, v17
	v_cvt_pk_bf16_f32 v17, v18, v19
	global_store_dwordx2 v57, v[16:17], s[16:17] offset:1024
	global_load_dwordx4 v[16:19], v[34:35], off offset:3072
	s_waitcnt vmcnt(0)
	v_pk_mul_f32 v[16:17], v[20:21], v[16:17]
	v_pk_mul_f32 v[20:21], v[22:23], v[46:47] op_sel_hi:[1,0]
	v_cvt_pk_bf16_f32 v16, v16, v17
	v_pk_mul_f32 v[18:19], v[20:21], v[18:19]
	s_nop 0
	v_cvt_pk_bf16_f32 v17, v18, v19
	global_store_dwordx2 v57, v[16:17], s[16:17] offset:1536

; #define GAS __attribute__((address_space(1)))
; DI float bf_lo(unsigned u) { return __uint_as_float(u << 16); }
; DI float bf_hi(unsigned u) { return __uint_as_float(u & 0xffff0000u); }
; DI void post_pass(int wv, const bf16_t* raw, long raw_row0, float* x, const float* gpost, const float* gpre, bf16_t* XN, int row_lo, int row_hi, const float* xin_p = nullptr, const float* xin_s = nullptr) {
;     ...
;     for (int row = row_lo + gw; row < row_hi; row += 2 * NGW) {
;         f32x4 v[2][4], xv[2][4]; float s[2] = {0.f, 0.f};
; #pragma unroll
;         for (int q = 0; q < 2; ++q) { const int rw = row + q * NGW;
;             const GAS u32x2* rr = (const GAS u32x2*)(raw + (size_t)(rw - raw_row0) * DM) + lane;
;             const GAS f32x4* xr = (const GAS f32x4*)(xin_p ? (rw < TOK_P ? xin_p + (size_t)rw * DM : xin_s + (size_t)(rw - TOK_P) * DM) : x + (size_t)rw * DM) + lane;
; #pragma unroll
;             for (int j = 0; j < 4; ++j) { const u32x2 w = rr[64 * j]; v[q][j] = (f32x4){bf_lo(w.x), bf_hi(w.x), bf_lo(w.y), bf_hi(w.y)}; xv[q][j] = xr[64 * j]; } }
; #pragma unroll
;         for (int q = 0; q < 2; ++q)
; #pragma unroll
;             for (int j = 0; j < 4; ++j) s[q] += (v[q][j].x * v[q][j].x + v[q][j].y * v[q][j].y) + (v[q][j].z * v[q][j].z + v[q][j].w * v[q][j].w);
; #pragma unroll
;         for (int q = 0; q < 2; ++q) { const int rw = row + q * NGW; GAS f32x4* xr = (GAS f32x4*)(x + (size_t)rw * DM) + lane;
;             const float rstd = __builtin_amdgcn_rsqf(wave_sum(s[q], lane) * (1.0f / DM) + RMS_EPS);
; #pragma unroll
;             for (int j = 0; j < 4; ++j) { const f32x4 gg = ((const GAS f32x4*)gpost)[lane + 64 * j]; xv[q][j] = xv[q][j] + v[q][j] * rstd * gg; xr[64 * j] = xv[q][j]; }
.LBB0_740:
	s_ashr_i32 s7, s6, 31
	s_lshl_b64 s[16:17], s[6:7], 11
	s_add_u32 s10, s22, s16
	s_addc_u32 s11, s23, s17
	v_lshlrev_b32_e32 v54, 3, v32
	global_load_dwordx2 v[0:1], v54, s[10:11] offset:1536 nt
	global_load_dwordx2 v[2:3], v54, s[10:11] nt
	global_load_dwordx2 v[12:13], v54, s[10:11] offset:512 nt
	global_load_dwordx2 v[14:15], v54, s[10:11] offset:1024 nt
	s_lshl_b64 s[10:11], s[6:7], 12
	s_add_u32 s18, s21, s10
	v_lshlrev_b32_e32 v38, 4, v32
	s_addc_u32 s19, s20, s11
	global_load_dwordx4 v[4:7], v[36:37], off
	global_load_dwordx4 v[8:11], v38, s[18:19]
	s_add_i32 s10, s6, s72
	s_ashr_i32 s11, s10, 31
	s_lshl_b64 s[12:13], s[10:11], 11
	s_add_u32 s6, s22, s12
	s_addc_u32 s7, s23, s13
	s_lshl_b64 s[14:15], s[10:11], 12
	s_add_u32 s14, s21, s14
	s_addc_u32 s15, s20, s15
	v_cndmask_b32_e64 v39, 0, 1, s[8:9]
	s_andn2_b64 vcc, exec, s[8:9]
	s_waitcnt vmcnt(0)
	v_lshlrev_b32_e32 v61, 16, v0
	v_and_b32_e32 v17, 0xffff0000, v2
	v_and_b32_e32 v19, 0xffff0000, v3
	v_and_b32_e32 v63, 0xffff0000, v0
	v_lshlrev_b32_e32 v64, 16, v1
	v_and_b32_e32 v65, 0xffff0000, v1
	v_lshlrev_b32_e32 v16, 16, v2
	v_lshlrev_b32_e32 v18, 16, v3
	v_lshlrev_b32_e32 v24, 16, v12
	v_and_b32_e32 v27, 0xffff0000, v13
	v_and_b32_e32 v26, 0xffff0000, v12
	v_mul_f32_e32 v0, v19, v19
	v_mul_f32_e32 v12, v17, v17
	v_mov_b32_e32 v1, v61
	v_lshlrev_b32_e32 v25, 16, v13
	v_and_b32_e32 v57, 0xffff0000, v14
	v_and_b32_e32 v59, 0xffff0000, v15
	v_pk_mul_f32 v[2:3], v[26:27], v[26:27]
	v_pk_fma_f32 v[22:23], v[18:19], v[18:19], v[0:1] op_sel_hi:[1,1,0]
	v_pk_fma_f32 v[12:13], v[16:17], v[16:17], v[12:13] op_sel_hi:[1,1,0]
	v_lshlrev_b32_e32 v56, 16, v14
	v_lshlrev_b32_e32 v58, 16, v15
	v_mul_f32_e32 v14, v57, v57
	v_mul_f32_e32 v20, v59, v59
	v_pk_fma_f32 v[2:3], v[24:25], v[24:25], v[2:3]
	v_mov_b32_e32 v60, v12
	v_mov_b32_e32 v0, v22
	v_mul_f32_e32 v28, v63, v63
	v_mul_f32_e32 v29, v64, v64
	v_mul_f32_e32 v30, v65, v65
	v_pk_fma_f32 v[14:15], v[56:57], v[56:57], v[14:15] op_sel_hi:[1,1,0]
	v_pk_fma_f32 v[20:21], v[58:59], v[58:59], v[20:21] op_sel_hi:[1,1,0]
	v_pk_add_f32 v[12:13], v[12:13], v[22:23]
	v_pk_add_f32 v[2:3], v[2:3], v[2:3] op_sel:[0,1] op_sel_hi:[1,0]
	v_pk_mul_f32 v[0:1], v[60:61], v[0:1]
	v_mov_b32_e32 v15, v29
	v_mov_b32_e32 v21, v30
	v_mov_b32_e32 v3, v28
	v_mov_b32_e32 v13, v1
	v_pk_add_f32 v[14:15], v[14:15], v[20:21]
	v_pk_add_f32 v[0:1], v[12:13], v[2:3]
	v_mov_b32_e32 v28, v25
	v_pk_add_f32 v[0:1], v[0:1], v[14:15]
	global_load_dwordx4 v[12:15], v38, s[18:19] offset:1024
	v_add_f32_e32 v0, v0, v1
	ds_bpermute_b32 v1, v33, v0
	global_load_dwordx2 v[44:45], v54, s[6:7] nt
	global_load_dwordx2 v[42:43], v54, s[6:7] offset:512 nt
	global_load_dwordx2 v[40:41], v54, s[6:7] offset:1024 nt
	global_load_dwordx2 v[46:47], v54, s[6:7] offset:1536 nt
	v_mov_b32_e32 v29, v27
	v_mov_b32_e32 v25, v26
	s_waitcnt lgkmcnt(0)
	v_add_f32_e32 v0, v0, v1
	ds_bpermute_b32 v1, v49, v0
	v_mov_b32_e32 v62, v61
	v_cmp_ne_u32_e64 s[6:7], 1, v39
	s_waitcnt lgkmcnt(0)
	v_add_f32_e32 v0, v0, v1
	ds_bpermute_b32 v1, v50, v0
	s_waitcnt lgkmcnt(0)
	v_add_f32_e32 v0, v0, v1
	ds_bpermute_b32 v1, v51, v0
	s_waitcnt lgkmcnt(0)
	v_add_f32_e32 v0, v0, v1
	ds_bpermute_b32 v1, v52, v0
	s_waitcnt lgkmcnt(0)
	v_add_f32_e32 v0, v0, v1
	ds_bpermute_b32 v1, v53, v0
	s_waitcnt lgkmcnt(0)
	v_add_f32_e32 v0, v0, v1
	v_fmamk_f32 v0, v0, 0x3a800000, v174
	v_rsq_f32_e32 v48, v0
	global_load_dwordx4 v[0:3], v38, s[14:15]
	v_pk_mul_f32 v[16:17], v[48:49], v[16:17] op_sel_hi:[0,1]
	v_pk_mul_f32 v[18:19], v[48:49], v[18:19] op_sel_hi:[0,1]
	v_pk_fma_f32 v[18:19], v[6:7], v[18:19], v[10:11]
	v_pk_fma_f32 v[16:17], v[4:5], v[16:17], v[8:9]
	global_store_dwordx4 v38, v[16:19], s[18:19]
	global_load_dwordx4 v[8:11], v[36:37], off offset:1024
	global_load_dwordx4 v[20:23], v38, s[18:19] offset:2048
	global_load_dwordx4 v[4:7], v38, s[14:15] offset:1024
	v_pk_mul_f32 v[26:27], v[48:49], v[28:29] op_sel_hi:[0,1]
	v_pk_mul_f32 v[24:25], v[48:49], v[24:25] op_sel_hi:[0,1]
	v_pk_mul_f32 v[58:59], v[48:49], v[58:59] op_sel_hi:[0,1]
	v_pk_mul_f32 v[56:57], v[48:49], v[56:57] op_sel_hi:[0,1]
	v_pk_mul_f32 v[60:61], v[48:49], v[64:65] op_sel_hi:[0,1]
	v_pk_mul_f32 v[62:63], v[48:49], v[62:63] op_sel_hi:[0,1]
	s_waitcnt vmcnt(2)
	v_pk_fma_f32 v[24:25], v[8:9], v[24:25], v[12:13]
	v_pk_fma_f32 v[26:27], v[10:11], v[26:27], v[14:15]
	global_store_dwordx4 v38, v[24:27], s[18:19] offset:1024
	global_load_dwordx4 v[12:15], v[36:37], off offset:2048
	global_load_dwordx4 v[28:31], v38, s[18:19] offset:3072
	global_load_dwordx4 v[8:11], v38, s[14:15] offset:2048
	s_waitcnt vmcnt(2)
	v_pk_fma_f32 v[20:21], v[12:13], v[56:57], v[20:21]
	v_pk_fma_f32 v[22:23], v[14:15], v[58:59], v[22:23]
	global_store_dwordx4 v38, v[20:23], s[18:19] offset:2048
	global_load_dwordx4 v[56:59], v[36:37], off offset:3072
	global_load_dwordx4 v[12:15], v38, s[14:15] offset:3072
	s_waitcnt vmcnt(1)
	v_pk_fma_f32 v[28:29], v[56:57], v[62:63], v[28:29]
	v_pk_fma_f32 v[30:31], v[58:59], v[60:61], v[30:31]
	global_store_dwordx4 v38, v[28:31], s[18:19] offset:3072
	s_cbranch_vccnz .LBB0_742
; #define GAS __attribute__((address_space(1)))
; DI unsigned pk2(float lo, float hi) { f32x2 v = {lo, hi}; bf16x2_t b = __builtin_convertvector(v, bf16x2_t); return __builtin_bit_cast(unsigned, b); }
; DI void norm_row_bf16(const f32x4 (&v)[4], const float* g, bf16_t* orow, int lane) {
;     float s = 0.f;
; #pragma unroll
;     for (int j = 0; j < 4; ++j) s += (v[j].x * v[j].x + v[j].y * v[j].y) + (v[j].z * v[j].z + v[j].w * v[j].w);
;     const float rstd = __builtin_amdgcn_rsqf(wave_sum(s, lane) * (1.0f / DM) + RMS_EPS);
;     GAS u32x2* o8 = (GAS u32x2*)orow + lane;
; #pragma unroll
;     for (int j = 0; j < 4; ++j) { const f32x4 gg = ((const GAS f32x4*)g)[lane + 64 * j]; u32x2 w; w.x = pk2(v[j].x * rstd * gg.x, v[j].y * rstd * gg.y); w.y = pk2(v[j].z * rstd * gg.z, v[j].w * rstd * gg.w); o8[64 * j] = w; }
; }
	v_pk_mul_f32 v[56:57], v[18:19], v[18:19]
	v_pk_mul_f32 v[58:59], v[16:17], v[16:17]
	v_mul_f32_e32 v48, v20, v20
	v_pk_mov_b32 v[60:61], v[58:59], v[56:57] op_sel:[1,0]
	v_mov_b32_e32 v59, v57
	v_pk_add_f32 v[56:57], v[60:61], v[58:59]
	v_pk_mul_f32 v[58:59], v[26:27], v[26:27]
	v_pk_mul_f32 v[60:61], v[24:25], v[24:25]
	v_pk_add_f32 v[56:57], v[56:57], v[56:57] op_sel_hi:[0,1]
	v_pk_mov_b32 v[62:63], v[60:61], v[58:59] op_sel:[1,0]
	v_mov_b32_e32 v61, v59
	v_pk_add_f32 v[58:59], v[62:63], v[60:61]
	v_pk_fma_f32 v[60:61], v[20:21], v[20:21], v[48:49] op_sel_hi:[1,1,0]
	v_mul_f32_e32 v48, v22, v22
	v_pk_add_f32 v[58:59], v[58:59], v[58:59] op_sel_hi:[0,1]
	v_pk_fma_f32 v[62:63], v[22:23], v[22:23], v[48:49] op_sel_hi:[1,1,0]
	v_mul_f32_e32 v60, v28, v28
	v_mul_f32_e32 v62, v29, v29
	v_mul_f32_e32 v56, v30, v30
	v_mul_f32_e32 v58, v31, v31
	v_pk_add_f32 v[60:61], v[60:61], v[62:63]
	v_pk_add_f32 v[56:57], v[56:57], v[58:59]
	s_add_u32 s16, s24, s16
	v_pk_add_f32 v[56:57], v[60:61], v[56:57]
	s_addc_u32 s17, s25, s17
	v_add_f32_e32 v39, v56, v57
	global_load_dwordx4 v[56:59], v[34:35], off
	ds_bpermute_b32 v48, v33, v39
	s_waitcnt lgkmcnt(0)
	v_add_f32_e32 v39, v39, v48
	ds_bpermute_b32 v48, v49, v39
	s_waitcnt lgkmcnt(0)
	v_add_f32_e32 v39, v39, v48
	ds_bpermute_b32 v48, v50, v39
	s_waitcnt lgkmcnt(0)
	v_add_f32_e32 v39, v39, v48
	ds_bpermute_b32 v48, v51, v39
	s_waitcnt lgkmcnt(0)
	v_add_f32_e32 v39, v39, v48
	ds_bpermute_b32 v48, v52, v39
	s_waitcnt lgkmcnt(0)
	v_add_f32_e32 v39, v39, v48
	ds_bpermute_b32 v48, v53, v39
	s_waitcnt lgkmcnt(0)
	v_add_f32_e32 v39, v39, v48
	v_fmamk_f32 v39, v39, 0x3a800000, v174
	v_rsq_f32_e32 v48, v39
	s_nop 0
	v_pk_mul_f32 v[16:17], v[16:17], v[48:49] op_sel_hi:[1,0]
	v_pk_mul_f32 v[18:19], v[18:19], v[48:49] op_sel_hi:[1,0]
	v_pk_mul_f32 v[24:25], v[24:25], v[48:49] op_sel_hi:[1,0]
	v_pk_mul_f32 v[20:21], v[20:21], v[48:49] op_sel_hi:[1,0]
	s_waitcnt vmcnt(0)
	v_pk_mul_f32 v[16:17], v[56:57], v[16:17]
	v_pk_mul_f32 v[18:19], v[58:59], v[18:19]
	v_cvt_pk_bf16_f32 v16, v16, v17
	v_cvt_pk_bf16_f32 v17, v18, v19
	global_store_dwordx2 v54, v[16:17], s[16:17]
	global_load_dwordx4 v[16:19], v[34:35], off offset:1024
	s_waitcnt vmcnt(0)
	v_pk_mul_f32 v[16:17], v[16:17], v[24:25]
	v_pk_mul_f32 v[24:25], v[26:27], v[48:49] op_sel_hi:[1,0]
	v_cvt_pk_bf16_f32 v16, v16, v17
	v_pk_mul_f32 v[18:19], v[18:19], v[24:25]
	s_nop 0
	v_cvt_pk_bf16_f32 v17, v18, v19
	global_store_dwordx2 v54, v[16:17], s[16:17] offset:512
	global_load_dwordx4 v[16:19], v[34:35], off offset:2048
	s_waitcnt vmcnt(0)
	v_pk_mul_f32 v[16:17], v[16:17], v[20:21]
	v_pk_mul_f32 v[20:21], v[22:23], v[48:49] op_sel_hi:[1,0]
	v_cvt_pk_bf16_f32 v16, v16, v17
	v_pk_mul_f32 v[18:19], v[18:19], v[20:21]
	v_pk_mul_f32 v[20:21], v[28:29], v[48:49] op_sel_hi:[1,0]
	v_cvt_pk_bf16_f32 v17, v18, v19
	global_store_dwordx2 v54, v[16:17], s[16:17] offset:1024
	global_load_dwordx4 v[16:19], v[34:35], off offset:3072
	s_waitcnt vmcnt(0)
	v_pk_mul_f32 v[16:17], v[20:21], v[16:17]
	v_pk_mul_f32 v[20:21], v[30:31], v[48:49] op_sel_hi:[1,0]
	v_cvt_pk_bf16_f32 v16, v16, v17
	v_pk_mul_f32 v[18:19], v[20:21], v[18:19]
	s_nop 0
	v_cvt_pk_bf16_f32 v17, v18, v19
	global_store_dwordx2 v54, v[16:17], s[16:17] offset:1536

; #define GAS __attribute__((address_space(1)))
; DI float bf_lo(unsigned u) { return __uint_as_float(u << 16); }
; DI float bf_hi(unsigned u) { return __uint_as_float(u & 0xffff0000u); }
; DI void post_pass(int wv, const bf16_t* raw, long raw_row0, float* x, const float* gpost, const float* gpre, bf16_t* XN, int row_lo, int row_hi, const float* xin_p = nullptr, const float* xin_s = nullptr) {
;     ...
;     for (int row = row_lo + gw; row < row_hi; row += 2 * NGW) {
;         f32x4 v[2][4], xv[2][4]; float s[2] = {0.f, 0.f};
; #pragma unroll
;         for (int q = 0; q < 2; ++q) { const int rw = row + q * NGW;
;             const GAS u32x2* rr = (const GAS u32x2*)(raw + (size_t)(rw - raw_row0) * DM) + lane;
;             const GAS f32x4* xr = (const GAS f32x4*)(xin_p ? (rw < TOK_P ? xin_p + (size_t)rw * DM : xin_s + (size_t)(rw - TOK_P) * DM) : x + (size_t)rw * DM) + lane;
; #pragma unroll
;             for (int j = 0; j < 4; ++j) { const u32x2 w = rr[64 * j]; v[q][j] = (f32x4){bf_lo(w.x), bf_hi(w.x), bf_lo(w.y), bf_hi(w.y)}; xv[q][j] = xr[64 * j]; } }
; #pragma unroll
;         for (int q = 0; q < 2; ++q)
; #pragma unroll
;             for (int j = 0; j < 4; ++j) s[q] += (v[q][j].x * v[q][j].x + v[q][j].y * v[q][j].y) + (v[q][j].z * v[q][j].z + v[q][j].w * v[q][j].w);
; #pragma unroll
;         for (int q = 0; q < 2; ++q) { const int rw = row + q * NGW; GAS f32x4* xr = (GAS f32x4*)(x + (size_t)rw * DM) + lane;
;             const float rstd = __builtin_amdgcn_rsqf(wave_sum(s[q], lane) * (1.0f / DM) + RMS_EPS);
; #pragma unroll
;             for (int j = 0; j < 4; ++j) { const f32x4 gg = ((const GAS f32x4*)gpost)[lane + 64 * j]; xv[q][j] = xv[q][j] + v[q][j] * rstd * gg; xr[64 * j] = xv[q][j]; }
.LBB0_914:
	s_add_i32 s22, s46, s33
	s_ashr_i32 s23, s22, 31
	s_sub_u32 s6, s22, s45
	s_subb_u32 s7, s23, s50
	s_lshl_b64 s[6:7], s[6:7], 11
	s_add_u32 s6, s30, s6
	s_addc_u32 s7, s31, s7
	v_lshlrev_b32_e32 v52, 3, v32
	global_load_dwordx2 v[0:1], v52, s[6:7] offset:1536 nt
	global_load_dwordx2 v[2:3], v52, s[6:7] nt
	global_load_dwordx2 v[12:13], v52, s[6:7] offset:512 nt
	global_load_dwordx2 v[14:15], v52, s[6:7] offset:1024 nt
	s_lshl_b64 s[6:7], s[22:23], 12
	s_add_u32 s24, s27, s6
	v_lshlrev_b32_e32 v192, 4, v32
	s_addc_u32 s25, s26, s7
	global_load_dwordx4 v[4:7], v[36:37], off
	global_load_dwordx4 v[8:11], v192, s[24:25]
	s_add_i32 s18, s52, s33
	s_ashr_i32 s19, s18, 31
	s_sub_u32 s6, s18, s45
	s_subb_u32 s7, s19, s50
	s_lshl_b64 s[6:7], s[6:7], 11
	s_add_u32 s6, s30, s6
	s_addc_u32 s7, s31, s7
	s_lshl_b64 s[20:21], s[18:19], 12
	s_add_u32 s20, s27, s20
	s_addc_u32 s21, s26, s21
	v_cndmask_b32_e64 v53, 0, 1, s[8:9]
	s_andn2_b64 vcc, exec, s[8:9]
	s_waitcnt vmcnt(5)
	v_lshlrev_b32_e32 v59, 16, v0
	s_waitcnt vmcnt(4)
	v_and_b32_e32 v17, 0xffff0000, v2
	v_and_b32_e32 v19, 0xffff0000, v3
	v_and_b32_e32 v61, 0xffff0000, v0
	v_lshlrev_b32_e32 v62, 16, v1
	v_and_b32_e32 v63, 0xffff0000, v1
	v_lshlrev_b32_e32 v16, 16, v2
	v_lshlrev_b32_e32 v18, 16, v3
	s_waitcnt vmcnt(3)
	v_lshlrev_b32_e32 v24, 16, v12
	v_and_b32_e32 v27, 0xffff0000, v13
	v_and_b32_e32 v26, 0xffff0000, v12
	v_mul_f32_e32 v0, v19, v19
	v_mul_f32_e32 v12, v17, v17
	v_mov_b32_e32 v1, v59
	v_lshlrev_b32_e32 v25, 16, v13
	s_waitcnt vmcnt(2)
	v_and_b32_e32 v55, 0xffff0000, v14
	v_and_b32_e32 v57, 0xffff0000, v15
	v_pk_mul_f32 v[2:3], v[26:27], v[26:27]
	v_pk_fma_f32 v[22:23], v[18:19], v[18:19], v[0:1] op_sel_hi:[1,1,0]
	v_pk_fma_f32 v[12:13], v[16:17], v[16:17], v[12:13] op_sel_hi:[1,1,0]
	v_lshlrev_b32_e32 v54, 16, v14
	v_lshlrev_b32_e32 v56, 16, v15
	v_mul_f32_e32 v14, v55, v55
	v_mul_f32_e32 v20, v57, v57
	v_pk_fma_f32 v[2:3], v[24:25], v[24:25], v[2:3]
	v_mov_b32_e32 v58, v12
	v_mov_b32_e32 v0, v22
	v_mul_f32_e32 v28, v61, v61
	v_mul_f32_e32 v29, v62, v62
	v_mul_f32_e32 v30, v63, v63
	v_pk_fma_f32 v[14:15], v[54:55], v[54:55], v[14:15] op_sel_hi:[1,1,0]
	v_pk_fma_f32 v[20:21], v[56:57], v[56:57], v[20:21] op_sel_hi:[1,1,0]
	v_pk_add_f32 v[12:13], v[12:13], v[22:23]
	v_pk_add_f32 v[2:3], v[2:3], v[2:3] op_sel:[0,1] op_sel_hi:[1,0]
	v_pk_mul_f32 v[0:1], v[58:59], v[0:1]
	v_mov_b32_e32 v15, v29
	v_mov_b32_e32 v21, v30
	v_mov_b32_e32 v3, v28
	v_mov_b32_e32 v13, v1
	v_pk_add_f32 v[14:15], v[14:15], v[20:21]
	v_pk_add_f32 v[0:1], v[12:13], v[2:3]
	v_mov_b32_e32 v28, v25
	v_pk_add_f32 v[0:1], v[0:1], v[14:15]
	global_load_dwordx4 v[12:15], v192, s[24:25] offset:1024
	v_add_f32_e32 v0, v0, v1
	ds_bpermute_b32 v1, v33, v0
	global_load_dwordx2 v[42:43], v52, s[6:7] nt
	global_load_dwordx2 v[40:41], v52, s[6:7] offset:512 nt
	global_load_dwordx2 v[38:39], v52, s[6:7] offset:1024 nt
	global_load_dwordx2 v[44:45], v52, s[6:7] offset:1536 nt
	v_mov_b32_e32 v29, v27
	v_mov_b32_e32 v25, v26
	s_waitcnt lgkmcnt(0)
	v_add_f32_e32 v0, v0, v1
	ds_bpermute_b32 v1, v47, v0
	v_mov_b32_e32 v60, v59
	v_cmp_ne_u32_e64 s[6:7], 1, v53
	s_waitcnt lgkmcnt(0)
	v_add_f32_e32 v0, v0, v1
	ds_bpermute_b32 v1, v48, v0
	s_waitcnt lgkmcnt(0)
	v_add_f32_e32 v0, v0, v1
	ds_bpermute_b32 v1, v49, v0
	s_waitcnt lgkmcnt(0)
	v_add_f32_e32 v0, v0, v1
	ds_bpermute_b32 v1, v50, v0
	s_waitcnt lgkmcnt(0)
	v_add_f32_e32 v0, v0, v1
	ds_bpermute_b32 v1, v51, v0
	s_waitcnt lgkmcnt(0)
	v_add_f32_e32 v0, v0, v1
	v_fmamk_f32 v0, v0, 0x3a800000, v174
	v_rsq_f32_e32 v46, v0
	global_load_dwordx4 v[0:3], v192, s[20:21]
	v_pk_mul_f32 v[16:17], v[46:47], v[16:17] op_sel_hi:[0,1]
	v_pk_mul_f32 v[18:19], v[46:47], v[18:19] op_sel_hi:[0,1]
	s_waitcnt vmcnt(6)
	v_pk_fma_f32 v[18:19], v[6:7], v[18:19], v[10:11]
	v_pk_fma_f32 v[16:17], v[4:5], v[16:17], v[8:9]
	global_store_dwordx4 v192, v[16:19], s[24:25]
	global_load_dwordx4 v[8:11], v[36:37], off offset:1024
	global_load_dwordx4 v[20:23], v192, s[24:25] offset:2048
	global_load_dwordx4 v[4:7], v192, s[20:21] offset:1024
	v_pk_mul_f32 v[26:27], v[46:47], v[28:29] op_sel_hi:[0,1]
	v_pk_mul_f32 v[24:25], v[46:47], v[24:25] op_sel_hi:[0,1]
	v_pk_mul_f32 v[56:57], v[46:47], v[56:57] op_sel_hi:[0,1]
	v_pk_mul_f32 v[54:55], v[46:47], v[54:55] op_sel_hi:[0,1]
	v_pk_mul_f32 v[58:59], v[46:47], v[62:63] op_sel_hi:[0,1]
	v_pk_mul_f32 v[60:61], v[46:47], v[60:61] op_sel_hi:[0,1]
	s_waitcnt vmcnt(2)
	v_pk_fma_f32 v[24:25], v[8:9], v[24:25], v[12:13]
	v_pk_fma_f32 v[26:27], v[10:11], v[26:27], v[14:15]
	global_store_dwordx4 v192, v[24:27], s[24:25] offset:1024
	global_load_dwordx4 v[12:15], v[36:37], off offset:2048
	global_load_dwordx4 v[28:31], v192, s[24:25] offset:3072
	global_load_dwordx4 v[8:11], v192, s[20:21] offset:2048
	s_waitcnt vmcnt(2)
	v_pk_fma_f32 v[20:21], v[12:13], v[54:55], v[20:21]
	v_pk_fma_f32 v[22:23], v[14:15], v[56:57], v[22:23]
	global_store_dwordx4 v192, v[20:23], s[24:25] offset:2048
	global_load_dwordx4 v[54:57], v[36:37], off offset:3072
	global_load_dwordx4 v[12:15], v192, s[20:21] offset:3072
	s_waitcnt vmcnt(1)
	v_pk_fma_f32 v[28:29], v[54:55], v[60:61], v[28:29]
	v_pk_fma_f32 v[30:31], v[56:57], v[58:59], v[30:31]
	global_store_dwordx4 v192, v[28:31], s[24:25] offset:3072
	s_cbranch_vccnz .LBB0_916
; #define GAS __attribute__((address_space(1)))
; DI unsigned pk2(float lo, float hi) { f32x2 v = {lo, hi}; bf16x2_t b = __builtin_convertvector(v, bf16x2_t); return __builtin_bit_cast(unsigned, b); }
; DI void norm_row_bf16(const f32x4 (&v)[4], const float* g, bf16_t* orow, int lane) {
;     float s = 0.f;
; #pragma unroll
;     for (int j = 0; j < 4; ++j) s += (v[j].x * v[j].x + v[j].y * v[j].y) + (v[j].z * v[j].z + v[j].w * v[j].w);
;     const float rstd = __builtin_amdgcn_rsqf(wave_sum(s, lane) * (1.0f / DM) + RMS_EPS);
;     GAS u32x2* o8 = (GAS u32x2*)orow + lane;
; #pragma unroll
;     for (int j = 0; j < 4; ++j) { const f32x4 gg = ((const GAS f32x4*)g)[lane + 64 * j]; u32x2 w; w.x = pk2(v[j].x * rstd * gg.x, v[j].y * rstd * gg.y); w.y = pk2(v[j].z * rstd * gg.z, v[j].w * rstd * gg.w); o8[64 * j] = w; }
; }
	v_pk_mul_f32 v[54:55], v[18:19], v[18:19]
	v_pk_mul_f32 v[56:57], v[16:17], v[16:17]
	v_mul_f32_e32 v46, v20, v20
	v_pk_mov_b32 v[58:59], v[56:57], v[54:55] op_sel:[1,0]
	v_mov_b32_e32 v57, v55
	v_pk_add_f32 v[54:55], v[58:59], v[56:57]
	v_pk_mul_f32 v[56:57], v[26:27], v[26:27]
	v_pk_mul_f32 v[58:59], v[24:25], v[24:25]
	v_pk_add_f32 v[54:55], v[54:55], v[54:55] op_sel_hi:[0,1]
	v_pk_mov_b32 v[60:61], v[58:59], v[56:57] op_sel:[1,0]
	v_mov_b32_e32 v59, v57
	v_pk_add_f32 v[56:57], v[60:61], v[58:59]
	v_pk_fma_f32 v[58:59], v[20:21], v[20:21], v[46:47] op_sel_hi:[1,1,0]
	v_mul_f32_e32 v46, v22, v22
	v_pk_add_f32 v[56:57], v[56:57], v[56:57] op_sel_hi:[0,1]
	v_pk_fma_f32 v[60:61], v[22:23], v[22:23], v[46:47] op_sel_hi:[1,1,0]
	v_mul_f32_e32 v58, v28, v28
	v_mul_f32_e32 v60, v29, v29
	v_mul_f32_e32 v54, v30, v30
	v_mul_f32_e32 v56, v31, v31
	v_pk_add_f32 v[58:59], v[58:59], v[60:61]
	v_pk_add_f32 v[54:55], v[54:55], v[56:57]
	s_lshl_b64 s[22:23], s[22:23], 11
	v_pk_add_f32 v[54:55], v[58:59], v[54:55]
	s_add_u32 s22, s28, s22
	v_add_f32_e32 v46, v54, v55
	global_load_dwordx4 v[54:57], v[34:35], off
	ds_bpermute_b32 v53, v33, v46
	s_addc_u32 s23, s29, s23
	s_waitcnt lgkmcnt(0)
	v_add_f32_e32 v46, v46, v53
	ds_bpermute_b32 v53, v47, v46
	s_waitcnt lgkmcnt(0)
	v_add_f32_e32 v46, v46, v53
	ds_bpermute_b32 v53, v48, v46
	s_waitcnt lgkmcnt(0)
	v_add_f32_e32 v46, v46, v53
	ds_bpermute_b32 v53, v49, v46
	s_waitcnt lgkmcnt(0)
	v_add_f32_e32 v46, v46, v53
	ds_bpermute_b32 v53, v50, v46
	s_waitcnt lgkmcnt(0)
	v_add_f32_e32 v46, v46, v53
	ds_bpermute_b32 v53, v51, v46
	s_waitcnt lgkmcnt(0)
	v_add_f32_e32 v46, v46, v53
	v_fmamk_f32 v46, v46, 0x3a800000, v174
	v_rsq_f32_e32 v46, v46
	s_nop 0
	v_pk_mul_f32 v[16:17], v[16:17], v[46:47] op_sel_hi:[1,0]
	v_pk_mul_f32 v[18:19], v[18:19], v[46:47] op_sel_hi:[1,0]
	v_pk_mul_f32 v[24:25], v[24:25], v[46:47] op_sel_hi:[1,0]
	v_pk_mul_f32 v[20:21], v[20:21], v[46:47] op_sel_hi:[1,0]
	s_waitcnt vmcnt(0)
	v_pk_mul_f32 v[16:17], v[54:55], v[16:17]
	v_pk_mul_f32 v[18:19], v[56:57], v[18:19]
	v_cvt_pk_bf16_f32 v16, v16, v17
	v_cvt_pk_bf16_f32 v17, v18, v19
	global_store_dwordx2 v52, v[16:17], s[22:23]
	global_load_dwordx4 v[16:19], v[34:35], off offset:1024
	s_waitcnt vmcnt(0)
	v_pk_mul_f32 v[16:17], v[16:17], v[24:25]
	v_pk_mul_f32 v[24:25], v[26:27], v[46:47] op_sel_hi:[1,0]
	v_cvt_pk_bf16_f32 v16, v16, v17
	v_pk_mul_f32 v[18:19], v[18:19], v[24:25]
	s_nop 0
	v_cvt_pk_bf16_f32 v17, v18, v19
	global_store_dwordx2 v52, v[16:17], s[22:23] offset:512
	global_load_dwordx4 v[16:19], v[34:35], off offset:2048
	s_waitcnt vmcnt(0)
	v_pk_mul_f32 v[16:17], v[16:17], v[20:21]
	v_pk_mul_f32 v[20:21], v[22:23], v[46:47] op_sel_hi:[1,0]
	v_cvt_pk_bf16_f32 v16, v16, v17
	v_pk_mul_f32 v[18:19], v[18:19], v[20:21]
	v_pk_mul_f32 v[20:21], v[28:29], v[46:47] op_sel_hi:[1,0]
	v_cvt_pk_bf16_f32 v17, v18, v19
	global_store_dwordx2 v52, v[16:17], s[22:23] offset:1024
	global_load_dwordx4 v[16:19], v[34:35], off offset:3072
	s_waitcnt vmcnt(0)
	v_pk_mul_f32 v[16:17], v[20:21], v[16:17]
	v_pk_mul_f32 v[20:21], v[30:31], v[46:47] op_sel_hi:[1,0]
	v_cvt_pk_bf16_f32 v16, v16, v17
	v_pk_mul_f32 v[18:19], v[20:21], v[18:19]
	s_nop 0
	v_cvt_pk_bf16_f32 v17, v18, v19
	global_store_dwordx2 v52, v[16:17], s[22:23] offset:1536
